# P5 start: 4 subgroups (blk>>3)&3 staggered by ~4us each to interleave epilogue HBM bursts with other subgroups' MFMA; stacks on v7
# baseline (speedup 1.0000x reference)
;     __device__ __forceinline__ bool next(int i, Unit& u) const { if (!base.next(i >> 1, u)) return false; if (i & 1) { u.pm += 64; u.pn += 8; } return true; }
;     __device__ bool next(int i, Unit& u) const {
;         const long L = (long)i * G + c; if (L >= nwg) return false;
;         int wgid = (int)L; { const int q = nwg / NXCD, r = nwg % NXCD, xcd = wgid % NXCD, off = wgid / NXCD; wgid = (xcd < r ? xcd * (q + 1) : r * (q + 1) + (xcd - r) * q) + off; }
; __device__ __forceinline__ void xcd_barrier(const XcdBarrier& b) {
;     ...
;             __builtin_amdgcn_fence(__ATOMIC_ACQUIRE, "agent");
;             asm volatile("s_waitcnt vmcnt(0)" ::: "memory");
;         }
;     }
;     __syncthreads();
.LBB0_663:
	s_or_b64 exec, exec, s[2:3]
	s_bfe_u32 s98, s62, 0x20003
	s_mul_i32 s98, s98, 1
	s_cmp_eq_u32 s98, 0
	s_cbranch_scc1 .Lstag_done_p5
.Lstag_loop_p5:
	s_sleep 127
	s_sub_u32 s98, s98, 1
	s_cmp_lg_u32 s98, 0
	s_cbranch_scc1 .Lstag_loop_p5
.Lstag_done_p5:
	v_readlane_b32 s4, v235, 7
	v_readlane_b32 s5, v235, 8
	s_mov_b64 s[2:3], -1
	s_and_b64 vcc, exec, s[4:5]
	s_waitcnt lgkmcnt(0)
	s_barrier
	s_cbranch_vccz .LBB0_874
	v_mov_b32_e32 v8, v186
	s_and_b64 vcc, exec, s[0:1]
	v_readfirstlane_b32 s5, v8
	s_cbranch_vccnz .LBB0_688
	s_ashr_i32 s33, s62, 31
	s_lshr_b32 s2, s33, 29
	s_add_i32 s6, s62, s2
	s_and_b32 s2, s6, -8
	s_sub_i32 s7, s62, s2
	s_cmp_gt_i32 s7, -1
	s_cbranch_scc0 .LBB0_667
	s_lshl_b32 s4, s7, 6
	s_cbranch_execz .LBB0_668
	s_branch .LBB0_669
